# grid barrier: XCD-last block bumps the top counter with a no-return atomic and all blocks wait on top_counter/8 (no returned atomic or generation word on the release path)
# baseline (speedup 1.0000x reference)
.LBB0_218:
	s_or_b64 exec, exec, s[2:3]
	v_cvt_f32_u32_e32 v4, v2
	s_waitcnt vmcnt(0)
	v_readfirstlane_b32 s2, v3
	v_sub_u32_e32 v3, 0, v2
	v_rcp_iflag_f32_e32 v4, v4
	v_add_u32_e32 v5, s2, v1
	v_mul_f32_e32 v4, 0x4f7ffffe, v4
	v_cvt_u32_f32_e32 v4, v4
	v_mul_lo_u32 v1, v3, v4
	v_mul_hi_u32 v1, v4, v1
	v_add_u32_e32 v1, v4, v1
	v_mul_hi_u32 v1, v5, v1
	v_mul_lo_u32 v3, v1, v2
	v_sub_u32_e32 v3, v5, v3
	v_add_u32_e32 v4, 1, v1
	v_cmp_ge_u32_e32 vcc, v3, v2
	s_nop 1
	v_cndmask_b32_e32 v1, v1, v4, vcc
	v_sub_u32_e32 v4, v3, v2
	v_cndmask_b32_e32 v3, v3, v4, vcc
	v_add_u32_e32 v4, 1, v1
	v_cmp_ge_u32_e32 vcc, v3, v2
	v_add_u32_e32 v3, 1, v5
	s_nop 0
	v_cndmask_b32_e32 v1, v1, v4, vcc
	v_mul_lo_u32 v4, v2, v1
	v_add_u32_e32 v2, v4, v2
	v_cmp_ne_u32_e32 vcc, v3, v2
	s_cbranch_vccnz .Lgs1_poll
	buffer_wbl2 sc1
	s_waitcnt vmcnt(0) lgkmcnt(0)
	v_mov_b32_e32 v10, 0
	v_mov_b32_e32 v11, 1
	s_add_u32 s6, s24, 0x3400
	s_addc_u32 s7, s25, 0
	global_atomic_add v10, v11, s[6:7]
.Lgs1_poll:
	s_mov_b64 vcc, exec
	s_and_saveexec_b64 s[2:3], vcc
	s_xor_b64 s[2:3], exec, s[2:3]
	s_cbranch_execz .LBB0_232
	s_add_u32 s6, s24, 0x3400
	s_waitcnt lgkmcnt(0)
	v_mov_b32_e32 v0, 0
	s_addc_u32 s7, s25, 0
	s_nop 4
	global_load_dword v2, v0, s[6:7] sc1
	s_waitcnt vmcnt(0)
	v_lshrrev_b32_e32 v2, 3, v2
	v_cmp_eq_u32_e32 vcc, v2, v1
	s_and_saveexec_b64 s[6:7], vcc
	s_cbranch_execz .LBB0_231
	s_mov_b32 s19, 1
	s_mov_b64 s[8:9], 0
	s_branch .LBB0_222

.LBB0_226:
	s_add_u32 s12, s24, 0x3400
	s_addc_u32 s13, s25, 0
	s_add_i32 s19, s19, 1
	s_mov_b64 s[14:15], -1
	s_nop 2
	global_load_dword v2, v0, s[12:13] sc1
	s_waitcnt vmcnt(0)
	v_lshrrev_b32_e32 v2, 3, v2
	v_cmp_ne_u32_e32 vcc, v2, v1
	s_orn2_b64 s[12:13], vcc, exec
	s_branch .LBB0_221

.LBB0_292:
	s_or_b64 exec, exec, s[12:13]
	v_cvt_f32_u32_e32 v5, v2
	s_waitcnt vmcnt(0)
	v_readfirstlane_b32 s12, v4
	v_sub_u32_e32 v4, 0, v2
	v_rcp_iflag_f32_e32 v5, v5
	v_add_u32_e32 v6, s12, v1
	v_mul_f32_e32 v5, 0x4f7ffffe, v5
	v_cvt_u32_f32_e32 v5, v5
	v_mul_lo_u32 v1, v4, v5
	v_mul_hi_u32 v1, v5, v1
	v_add_u32_e32 v1, v5, v1
	v_mul_hi_u32 v1, v6, v1
	v_mul_lo_u32 v4, v1, v2
	v_sub_u32_e32 v4, v6, v4
	v_add_u32_e32 v5, 1, v1
	v_cmp_ge_u32_e32 vcc, v4, v2
	s_nop 1
	v_cndmask_b32_e32 v1, v1, v5, vcc
	v_sub_u32_e32 v5, v4, v2
	v_cndmask_b32_e32 v4, v4, v5, vcc
	v_add_u32_e32 v5, 1, v1
	v_cmp_ge_u32_e32 vcc, v4, v2
	v_add_u32_e32 v4, 1, v6
	s_nop 0
	v_cndmask_b32_e32 v1, v1, v5, vcc
	v_mul_lo_u32 v5, v2, v1
	v_add_u32_e32 v2, v5, v2
	v_cmp_ne_u32_e32 vcc, v4, v2
	s_cbranch_vccnz .Lgs2_poll
	buffer_wbl2 sc1
	s_waitcnt vmcnt(0) lgkmcnt(0)
	v_mov_b32_e32 v10, 0
	v_mov_b32_e32 v11, 1
	s_add_u32 s40, s24, 0x3400
	s_addc_u32 s41, s25, 0
	global_atomic_add v10, v11, s[40:41]
.Lgs2_poll:
	s_mov_b64 vcc, exec
	s_and_saveexec_b64 s[12:13], vcc
	s_xor_b64 s[12:13], exec, s[12:13]
	s_cbranch_execz .LBB0_306
	v_readlane_b32 s40, v236, 34
	v_readlane_b32 s41, v236, 35
	s_waitcnt lgkmcnt(0)
	s_nop 3
	global_load_dword v0, v3, s[40:41] sc1
	s_waitcnt vmcnt(0)
	v_lshrrev_b32_e32 v0, 3, v0
	v_cmp_eq_u32_e32 vcc, v0, v1
	s_and_saveexec_b64 s[40:41], vcc
	s_cbranch_execz .LBB0_305
	s_mov_b32 s15, 1
	s_mov_b64 s[42:43], 0
	s_branch .LBB0_296

.LBB0_300:
	v_readlane_b32 s46, v236, 34
	v_readlane_b32 s47, v236, 35
	s_add_i32 s15, s15, 1
	s_mov_b64 s[48:49], -1
	s_nop 2
	global_load_dword v0, v3, s[46:47] sc1
	s_waitcnt vmcnt(0)
	v_lshrrev_b32_e32 v0, 3, v0
	v_cmp_ne_u32_e32 vcc, v0, v1
	s_orn2_b64 s[46:47], vcc, exec
	s_branch .LBB0_295

.Lgs3_poll:
	s_mov_b64 vcc, exec
	s_and_saveexec_b64 s[12:13], vcc
	s_xor_b64 s[12:13], exec, s[12:13]
	s_cbranch_execz .LBB0_513
	v_readlane_b32 s40, v236, 34
	v_readlane_b32 s41, v236, 35
	s_waitcnt lgkmcnt(0)
	s_nop 3
	global_load_dword v0, v3, s[40:41] sc1
	s_waitcnt vmcnt(0)
	v_lshrrev_b32_e32 v0, 3, v0
	v_cmp_eq_u32_e32 vcc, v0, v1
	s_and_saveexec_b64 s[40:41], vcc
	s_cbranch_execz .LBB0_512
	s_mov_b32 s34, 1
	s_mov_b64 s[42:43], 0
	s_branch .LBB0_503

.LBB0_507:
	v_readlane_b32 s46, v236, 34
	v_readlane_b32 s47, v236, 35
	s_add_i32 s34, s34, 1
	s_mov_b64 s[48:49], -1
	s_nop 2
	global_load_dword v0, v3, s[46:47] sc1
	s_waitcnt vmcnt(0)
	v_lshrrev_b32_e32 v0, 3, v0
	v_cmp_ne_u32_e32 vcc, v0, v1
	s_orn2_b64 s[46:47], vcc, exec
	s_branch .LBB0_502

.LBB0_1081:
	s_or_b64 exec, exec, s[2:3]
	v_cvt_f32_u32_e32 v4, v2
	s_waitcnt vmcnt(0)
	v_readfirstlane_b32 s2, v3
	v_sub_u32_e32 v3, 0, v2
	v_rcp_iflag_f32_e32 v4, v4
	v_add_u32_e32 v5, s2, v1
	v_mul_f32_e32 v4, 0x4f7ffffe, v4
	v_cvt_u32_f32_e32 v4, v4
	v_mul_lo_u32 v1, v3, v4
	v_mul_hi_u32 v1, v4, v1
	v_add_u32_e32 v1, v4, v1
	v_mul_hi_u32 v1, v5, v1
	v_mul_lo_u32 v3, v1, v2
	v_sub_u32_e32 v3, v5, v3
	v_add_u32_e32 v4, 1, v1
	v_cmp_ge_u32_e32 vcc, v3, v2
	s_nop 1
	v_cndmask_b32_e32 v1, v1, v4, vcc
	v_sub_u32_e32 v4, v3, v2
	v_cndmask_b32_e32 v3, v3, v4, vcc
	v_add_u32_e32 v4, 1, v1
	v_cmp_ge_u32_e32 vcc, v3, v2
	v_add_u32_e32 v3, 1, v5
	s_nop 0
	v_cndmask_b32_e32 v1, v1, v4, vcc
	v_mul_lo_u32 v4, v2, v1
	v_add_u32_e32 v2, v4, v2
	v_cmp_ne_u32_e32 vcc, v3, v2
	s_cbranch_vccnz .Lgs7_poll
	buffer_wbl2 sc1
	s_waitcnt vmcnt(0) lgkmcnt(0)
	v_mov_b32_e32 v10, 0
	v_mov_b32_e32 v11, 1
	s_add_u32 s4, s24, 0x3400
	s_addc_u32 s5, s25, 0
	global_atomic_add v10, v11, s[4:5]
.Lgs7_poll:
	s_mov_b64 vcc, exec
	s_and_saveexec_b64 s[2:3], vcc
	s_xor_b64 s[2:3], exec, s[2:3]
	s_cbranch_execz .LBB0_1095
	v_readlane_b32 s4, v236, 34
	s_waitcnt lgkmcnt(0)
	v_mov_b32_e32 v0, 0
	v_readlane_b32 s5, v236, 35
	s_nop 4
	global_load_dword v2, v0, s[4:5] sc1
	s_waitcnt vmcnt(0)
	v_lshrrev_b32_e32 v2, 3, v2
	v_cmp_eq_u32_e32 vcc, v2, v1
	s_and_saveexec_b64 s[4:5], vcc
	s_cbranch_execz .LBB0_1094
	s_mov_b32 s16, 1
	s_mov_b64 s[6:7], 0
	s_branch .LBB0_1085

.LBB0_1089:
	v_readlane_b32 s10, v236, 34
	v_readlane_b32 s11, v236, 35
	s_add_i32 s16, s16, 1
	s_mov_b64 s[12:13], -1
	s_nop 2
	global_load_dword v2, v0, s[10:11] sc1
	s_waitcnt vmcnt(0)
	v_lshrrev_b32_e32 v2, 3, v2
	v_cmp_ne_u32_e32 vcc, v2, v1
	s_orn2_b64 s[10:11], vcc, exec
	s_branch .LBB0_1084
